# DF loop: second-chain K fragments fetched ahead (12 reads up front + 4 as chain 1 frees registers); chain 2 starts without an exposed LDS round trip
# speedup vs baseline: 1.0113x; 1.0113x over previous
; #define SBAR() __builtin_amdgcn_sched_barrier(0)
; __device__ __forceinline__ int crow(int r, int hi) { return (r & 3) + 8 * (r >> 2) + 4 * hi; }
; #define KRD8(a, o_) do { KRD(a##0, kb0, (o_)); KRD(a##1, kb1, (o_)); KRD(a##2, kb2, (o_)); KRD(a##3, kb3, (o_)); KRD(a##4, kb0, (o_) + 128); KRD(a##5, kb1, (o_) + 128); KRD(a##6, kb2, (o_) + 128); KRD(a##7, kb3, (o_) + 128); } while (0)
; template <bool ALL16>
; __device__ __forceinline__ void qkt_b(f32x16& p0, f32x16& p1, unsigned kt, int r32, int hi, const bf16x8* qr) {
;     unsigned kb0 = kt + KSWZ(r32, (0 * 16 + hi * 8) * 2), kb1 = kt + KSWZ(r32, (1 * 16 + hi * 8) * 2), kb2 = kt + KSWZ(r32, (2 * 16 + hi * 8) * 2), kb3 = kt + KSWZ(r32, (3 * 16 + hi * 8) * 2);
;     ...
;     bf16x8 a0, a1, a2, a3, a4, a5, a6, a7;
;     p0 = f32x16{}; p1 = f32x16{};
;     if constexpr (ALL16) {
;         bf16x8 c0, c1, c2, c3, c4, c5, c6, c7;
;         KRD8(a, 0); KRD8(c, 8192);
;         asm volatile("s_waitcnt lgkmcnt(8)" ::: "memory"); SBAR();
;         KMMA8(p0, a);
;         asm volatile("s_waitcnt lgkmcnt(0)" ::: "memory"); SBAR();
;         KMMA8(p1, c);
;     } else {
;         KRD8(a, 0);
;         asm volatile("s_waitcnt lgkmcnt(0)" ::: "memory"); SBAR();
;         KMMA8(p0, a);
;         SBAR();
;         KRD8(a, 8192);
;         asm volatile("s_waitcnt lgkmcnt(0)" ::: "memory"); SBAR();
;         KMMA8(p1, a);
; template <bool FIXED>
; __device__ __forceinline__ void df_unit(LAS char* lds, bf16_t* QKV, const float* gsub, float lam, float post, int b, int h, int qb, int wave0, float mfix2) {
;     ...
;             if constexpr (FIXED) { constexpr float C2f = LOG2E * SCALE; alpha = 1.f;
; #pragma unroll
;                 for (int r = 0; r < 16; ++r) { p0[r] = __builtin_amdgcn_exp2f(fmaf(p0[r], C2f, mfix2)); p1[r] = __builtin_amdgcn_exp2f(fmaf(p1[r], C2f, mfix2)); } }
;             else {
;             partialSM(p0, p1, m_reg, alpha);
;             if (__any(alpha < 1.f)) { if (hi == 0) al_l[r32] = alpha; asm volatile("s_waitcnt lgkmcnt(0)" ::: "memory");
; #pragma unroll
;                 for (int r = 0; r < 16; ++r) { const float a = al_l[crow(r, hi)];
; #pragma unroll
;                     for (int d = 0; d < 8; ++d) o[d][r] *= a; } }
;             }
;             finishSM(p0, p1, alpha, l_reg, pa0, pa1, pa2, pa3);
;             pv_tile2<8>(o, vbase + bf * 4 * TILE + 2 * TILE, pa0, pa1, pa2, pa3);
.LBB0_147:
	s_sub_i32 s1, s19, 63
	s_cmp_gt_u32 s1, s33
	s_cbranch_scc1 .LBB0_144
	s_lshl_b32 s4, s0, 16
	s_add_i32 s0, s34, s4
	v_add_u32_e32 v0, s0, v206
	ds_read_b128 v[130:133], v0
	v_add_u32_e32 v217, s0, v207
	ds_read_b128 v[150:153], v217
	v_add_u32_e32 v233, s0, v208
	ds_read_b128 v[154:157], v233
	v_add_u32_e32 v246, s0, v209
	ds_read_b128 v[158:161], v246
	ds_read_b128 v[218:221], v0 offset:0x80
	ds_read_b128 v[234:237], v217 offset:0x80
	ds_read_b128 v[238:241], v233 offset:0x80
	ds_read_b128 v[242:245], v246 offset:0x80
	ds_read_b128 v[146:149], v0 offset:0x2000
	ds_read_b128 v[210:213], v217 offset:0x2000
	ds_read_b128 v[226:229], v233 offset:0x2000
	ds_read_b128 v[246:249], v246 offset:0x2000
	s_cmp_le_u32 s19, s15
	s_waitcnt lgkmcnt(4)
	v_mfma_f32_32x32x16_bf16 v[130:145], v[130:133], v[162:165], 0
	v_mfma_f32_32x32x16_bf16 v[130:145], v[150:153], v[166:169], v[130:145]
	v_mfma_f32_32x32x16_bf16 v[130:145], v[154:157], v[170:173], v[130:145]
	v_mfma_f32_32x32x16_bf16 v[130:145], v[158:161], v[174:177], v[130:145]
	v_mfma_f32_32x32x16_bf16 v[130:145], v[218:221], v[178:181], v[130:145]
	ds_read_b128 v[218:221], v0 offset:0x2080
	v_add_u32_e32 v0, s0, v209
	v_mfma_f32_32x32x16_bf16 v[130:145], v[234:237], v[182:185], v[130:145]
	ds_read_b128 v[234:237], v217 offset:0x2080
	v_mfma_f32_32x32x16_bf16 v[130:145], v[238:241], v[186:189], v[130:145]
	ds_read_b128 v[238:241], v233 offset:0x2080
	v_mfma_f32_32x32x16_bf16 v[130:145], v[242:245], v[190:193], v[130:145]
	ds_read_b128 v[242:245], v0 offset:0x2080
	s_cbranch_scc0 .Ldf_diag
	s_waitcnt lgkmcnt(4)
	v_mfma_f32_32x32x16_bf16 v[146:161], v[146:149], v[162:165], 0
	s_nop 3
	v_mfma_f32_32x32x16_bf16 v[146:161], v[210:213], v[166:169], v[146:161]
	s_nop 2
	v_fmamk_f32 v130, v130, 0x3e0293ee, v231
	v_fmamk_f32 v131, v131, 0x3e0293ee, v231
	v_exp_f32_e32 v130, v130
	v_exp_f32_e32 v131, v131
	v_mfma_f32_32x32x16_bf16 v[146:161], v[226:229], v[170:173], v[146:161]
	v_fmamk_f32 v132, v132, 0x3e0293ee, v231
	v_fmamk_f32 v133, v133, 0x3e0293ee, v231
	v_exp_f32_e32 v132, v132
	v_exp_f32_e32 v133, v133
	v_add_f32_e32 v217, 0, v130
	v_add_f32_e32 v217, v131, v217
	v_mfma_f32_32x32x16_bf16 v[146:161], v[246:249], v[174:177], v[146:161]
	v_fmamk_f32 v134, v134, 0x3e0293ee, v231
	v_fmamk_f32 v135, v135, 0x3e0293ee, v231
	v_exp_f32_e32 v134, v134
	v_exp_f32_e32 v135, v135
	v_add_f32_e32 v217, v132, v217
	v_add_f32_e32 v217, v133, v217
	s_waitcnt lgkmcnt(3)
	v_mfma_f32_32x32x16_bf16 v[146:161], v[218:221], v[178:181], v[146:161]
	v_fmamk_f32 v136, v136, 0x3e0293ee, v231
	v_fmamk_f32 v137, v137, 0x3e0293ee, v231
	v_exp_f32_e32 v136, v136
	v_exp_f32_e32 v137, v137
	v_add_f32_e32 v217, v134, v217
	v_add_f32_e32 v217, v135, v217
	s_waitcnt lgkmcnt(2)
	v_mfma_f32_32x32x16_bf16 v[146:161], v[234:237], v[182:185], v[146:161]
	v_fmamk_f32 v138, v138, 0x3e0293ee, v231
	v_fmamk_f32 v139, v139, 0x3e0293ee, v231
	v_exp_f32_e32 v138, v138
	v_exp_f32_e32 v139, v139
	v_add_f32_e32 v217, v136, v217
	v_add_f32_e32 v217, v137, v217
	s_waitcnt lgkmcnt(1)
	v_mfma_f32_32x32x16_bf16 v[146:161], v[238:241], v[186:189], v[146:161]
	v_fmamk_f32 v140, v140, 0x3e0293ee, v231
	v_fmamk_f32 v141, v141, 0x3e0293ee, v231
	v_exp_f32_e32 v140, v140
	v_exp_f32_e32 v141, v141
	v_add_f32_e32 v217, v138, v217
	v_add_f32_e32 v217, v139, v217
	s_waitcnt lgkmcnt(0)
	v_mfma_f32_32x32x16_bf16 v[146:161], v[242:245], v[190:193], v[146:161]
	v_fmamk_f32 v142, v142, 0x3e0293ee, v231
	v_fmamk_f32 v143, v143, 0x3e0293ee, v231
	v_exp_f32_e32 v142, v142
	v_exp_f32_e32 v143, v143
	v_add_f32_e32 v217, v140, v217
	v_add_f32_e32 v217, v141, v217
	v_fmamk_f32 v144, v144, 0x3e0293ee, v231
	v_fmamk_f32 v145, v145, 0x3e0293ee, v231
	v_exp_f32_e32 v144, v144
	v_exp_f32_e32 v145, v145
	v_add_f32_e32 v217, v142, v217
	v_add_f32_e32 v217, v143, v217
	v_add_f32_e32 v217, v144, v217
	v_add_f32_e32 v217, v145, v217
	v_cvt_pk_bf16_f32 v130, v130, v131
	v_cvt_pk_bf16_f32 v131, v132, v133
	v_cvt_pk_bf16_f32 v132, v134, v135
	v_cvt_pk_bf16_f32 v133, v136, v137
	v_cvt_pk_bf16_f32 v134, v138, v139
	v_cvt_pk_bf16_f32 v135, v140, v141
	v_cvt_pk_bf16_f32 v136, v142, v143
	v_cvt_pk_bf16_f32 v137, v144, v145
	v_permlane32_swap_b32_e32 v130, v132
	v_permlane32_swap_b32_e32 v131, v133
	v_permlane32_swap_b32_e32 v134, v136
	v_permlane32_swap_b32_e32 v135, v137
	v_fmamk_f32 v146, v146, 0x3e0293ee, v231
	v_fmamk_f32 v147, v147, 0x3e0293ee, v231
	v_exp_f32_e32 v146, v146
	v_exp_f32_e32 v147, v147
	v_fmamk_f32 v148, v148, 0x3e0293ee, v231
	v_fmamk_f32 v149, v149, 0x3e0293ee, v231
	v_exp_f32_e32 v148, v148
	v_exp_f32_e32 v149, v149
	v_add_f32_e32 v217, v146, v217
	v_add_f32_e32 v217, v147, v217
	v_fmamk_f32 v150, v150, 0x3e0293ee, v231
	v_fmamk_f32 v151, v151, 0x3e0293ee, v231
	v_exp_f32_e32 v150, v150
	v_exp_f32_e32 v151, v151
	v_add_f32_e32 v217, v148, v217
	v_add_f32_e32 v217, v149, v217
	v_fmamk_f32 v152, v152, 0x3e0293ee, v231
	v_fmamk_f32 v153, v153, 0x3e0293ee, v231
	v_exp_f32_e32 v152, v152
	v_exp_f32_e32 v153, v153
	v_add_f32_e32 v217, v150, v217
	v_add_f32_e32 v217, v151, v217
	v_fmamk_f32 v154, v154, 0x3e0293ee, v231
	v_fmamk_f32 v155, v155, 0x3e0293ee, v231
	v_exp_f32_e32 v154, v154
	v_exp_f32_e32 v155, v155
	v_add_f32_e32 v217, v152, v217
	v_add_f32_e32 v217, v153, v217
	v_fmamk_f32 v156, v156, 0x3e0293ee, v231
	v_fmamk_f32 v157, v157, 0x3e0293ee, v231
	v_exp_f32_e32 v156, v156
	v_exp_f32_e32 v157, v157
	v_add_f32_e32 v217, v154, v217
	v_add_f32_e32 v217, v155, v217
	v_fmamk_f32 v158, v158, 0x3e0293ee, v231
	v_fmamk_f32 v159, v159, 0x3e0293ee, v231
	v_exp_f32_e32 v158, v158
	v_exp_f32_e32 v159, v159
	v_add_f32_e32 v217, v156, v217
	v_add_f32_e32 v217, v157, v217
	v_fmamk_f32 v160, v160, 0x3e0293ee, v231
	v_fmamk_f32 v161, v161, 0x3e0293ee, v231
	v_exp_f32_e32 v160, v160
	v_exp_f32_e32 v161, v161
	v_add_f32_e32 v217, v158, v217
	v_add_f32_e32 v217, v159, v217
	s_nop 0
	v_add_f32_e32 v217, v160, v217
	v_add_f32_e32 v217, v161, v217
	v_cvt_pk_bf16_f32 v138, v146, v147
	v_cvt_pk_bf16_f32 v139, v148, v149
	v_cvt_pk_bf16_f32 v140, v150, v151
	v_cvt_pk_bf16_f32 v141, v152, v153
	v_cvt_pk_bf16_f32 v142, v154, v155
	v_cvt_pk_bf16_f32 v143, v156, v157
	v_cvt_pk_bf16_f32 v144, v158, v159
	v_cvt_pk_bf16_f32 v145, v160, v161
	s_nop 0
	v_permlane32_swap_b32_e32 v138, v140
	v_permlane32_swap_b32_e32 v139, v141
	v_permlane32_swap_b32_e32 v142, v144
	v_permlane32_swap_b32_e32 v143, v145
	s_branch .Ldf_pv
; #define SBAR() __builtin_amdgcn_sched_barrier(0)
; #define KRD8(a, o_) do { KRD(a##0, kb0, (o_)); KRD(a##1, kb1, (o_)); KRD(a##2, kb2, (o_)); KRD(a##3, kb3, (o_)); KRD(a##4, kb0, (o_) + 128); KRD(a##5, kb1, (o_) + 128); KRD(a##6, kb2, (o_) + 128); KRD(a##7, kb3, (o_) + 128); } while (0)
; template <bool ALL16>
; __device__ __forceinline__ void qkt_b(f32x16& p0, f32x16& p1, unsigned kt, int r32, int hi, const bf16x8* qr) {
;     ...
;     } else {
;         KRD8(a, 0);
;         asm volatile("s_waitcnt lgkmcnt(0)" ::: "memory"); SBAR();
;         KMMA8(p0, a);
;         SBAR();
;         KRD8(a, 8192);
;         asm volatile("s_waitcnt lgkmcnt(0)" ::: "memory"); SBAR();
;         KMMA8(p1, a);
; __device__ __forceinline__ void mask_incl(f32x16& p0, f32x16& p1, int dq) {
;     const float NEG = -__builtin_inff();
; #pragma unroll
;     for (int r = 0; r < 16; ++r) { const int c = (r & 3) + 8 * (r >> 2);
;         if (dq - c < 0) p0[r] = NEG;
;         if (dq - c - 32 < 0) p1[r] = NEG; }
; }
.Ldf_diag:
	s_waitcnt lgkmcnt(4)
	v_mfma_f32_32x32x16_bf16 v[146:161], v[146:149], v[162:165], 0
	v_mfma_f32_32x32x16_bf16 v[146:161], v[210:213], v[166:169], v[146:161]
	v_mfma_f32_32x32x16_bf16 v[146:161], v[226:229], v[170:173], v[146:161]
	v_mfma_f32_32x32x16_bf16 v[146:161], v[246:249], v[174:177], v[146:161]
	s_waitcnt lgkmcnt(3)
	v_mfma_f32_32x32x16_bf16 v[146:161], v[218:221], v[178:181], v[146:161]
	s_waitcnt lgkmcnt(2)
	v_mfma_f32_32x32x16_bf16 v[146:161], v[234:237], v[182:185], v[146:161]
	s_waitcnt lgkmcnt(1)
	v_mfma_f32_32x32x16_bf16 v[146:161], v[238:241], v[186:189], v[146:161]
	s_waitcnt lgkmcnt(0)
	v_mfma_f32_32x32x16_bf16 v[146:161], v[242:245], v[190:193], v[146:161]
	v_cmp_gt_i32_e64 s[94:95], 26, v215
	v_cmp_gt_i32_e64 s[96:97], 27, v215
	v_cmp_gt_i32_e64 s[92:93], 25, v215
	s_and_b64 s[94:95], s[96:97], s[94:95]
	v_cmp_gt_i32_e64 s[90:91], 24, v215
	s_and_b64 s[92:93], s[94:95], s[92:93]
	v_cmp_gt_i32_e64 s[88:89], 19, v215
	s_and_b64 s[90:91], s[92:93], s[90:91]
	v_cmp_gt_i32_e64 s[86:87], 18, v215
	s_and_b64 s[88:89], s[90:91], s[88:89]
	v_cmp_gt_i32_e64 s[84:85], 17, v215
	s_and_b64 s[86:87], s[88:89], s[86:87]
	v_cmp_gt_i32_e64 s[82:83], 16, v215
	s_and_b64 s[84:85], s[86:87], s[84:85]
	v_cmp_gt_i32_e64 s[80:81], 11, v215
	s_and_b64 s[82:83], s[84:85], s[82:83]
	v_cmp_gt_i32_e64 s[78:79], 10, v215
	s_and_b64 s[80:81], s[82:83], s[80:81]
	v_cmp_gt_i32_e64 s[76:77], 9, v215
	s_and_b64 s[78:79], s[80:81], s[78:79]
	v_cmp_gt_i32_e64 s[74:75], 8, v215
	s_and_b64 s[76:77], s[78:79], s[76:77]
	v_cmp_gt_i32_e64 s[72:73], 3, v215
	s_and_b64 s[74:75], s[76:77], s[74:75]
	v_cmp_gt_i32_e64 s[70:71], 2, v215
	s_and_b64 s[72:73], s[74:75], s[72:73]
	v_cmp_gt_i32_e64 s[66:67], 1, v215
	s_and_b64 s[70:71], s[72:73], s[70:71]
	v_cmp_gt_i32_e64 s[64:65], 0, v215
	s_and_b64 s[66:67], s[70:71], s[66:67]
	s_and_b64 s[64:65], s[66:67], s[64:65]
	v_cmp_gt_i32_e64 s[62:63], 58, v215
	v_cndmask_b32_e64 v130, v130, v225, s[64:65]
	v_cmp_gt_i32_e64 s[64:65], 59, v215
	v_cmp_gt_i32_e64 s[60:61], 57, v215
	s_and_b64 s[62:63], s[64:65], s[62:63]
	v_cmp_gt_i32_e64 s[58:59], 56, v215
	s_and_b64 s[60:61], s[62:63], s[60:61]
	v_cmp_gt_i32_e64 s[56:57], 51, v215
	s_and_b64 s[58:59], s[60:61], s[58:59]
	v_cmp_gt_i32_e64 s[54:55], 50, v215
	s_and_b64 s[56:57], s[58:59], s[56:57]
	v_cmp_gt_i32_e64 s[52:53], 49, v215
	s_and_b64 s[54:55], s[56:57], s[54:55]
	v_cmp_gt_i32_e64 s[50:51], 48, v215
	s_and_b64 s[52:53], s[54:55], s[52:53]
	v_cmp_gt_i32_e64 s[48:49], 43, v215
	s_and_b64 s[50:51], s[52:53], s[50:51]
	v_cmp_gt_i32_e64 s[46:47], 42, v215
	s_and_b64 s[48:49], s[50:51], s[48:49]
	v_cmp_gt_i32_e64 s[44:45], 41, v215
	s_and_b64 s[46:47], s[48:49], s[46:47]
	v_cmp_gt_i32_e64 s[42:43], 40, v215
	s_and_b64 s[44:45], s[46:47], s[44:45]
	v_cmp_gt_i32_e64 s[40:41], 35, v215
	s_and_b64 s[42:43], s[44:45], s[42:43]
	v_cmp_gt_i32_e64 s[36:37], 34, v215
	s_and_b64 s[40:41], s[42:43], s[40:41]
	v_cmp_gt_i32_e64 s[0:1], 33, v215
	s_and_b64 s[36:37], s[40:41], s[36:37]
	v_cmp_gt_i32_e32 vcc, 32, v215
	s_and_b64 s[0:1], s[36:37], s[0:1]
	s_and_b64 vcc, s[0:1], vcc
	v_cndmask_b32_e64 v145, v145, v225, s[96:97]
	v_cndmask_b32_e64 v144, v144, v225, s[94:95]
	v_cndmask_b32_e64 v143, v143, v225, s[92:93]
	v_cndmask_b32_e64 v142, v142, v225, s[90:91]
	v_cndmask_b32_e64 v141, v141, v225, s[88:89]
	v_cndmask_b32_e64 v140, v140, v225, s[86:87]
	v_cndmask_b32_e64 v139, v139, v225, s[84:85]
	v_cndmask_b32_e64 v138, v138, v225, s[82:83]
	v_cndmask_b32_e64 v137, v137, v225, s[80:81]
	v_cndmask_b32_e64 v136, v136, v225, s[78:79]
	v_cndmask_b32_e64 v135, v135, v225, s[76:77]
	v_cndmask_b32_e64 v134, v134, v225, s[74:75]
	v_cndmask_b32_e64 v133, v133, v225, s[72:73]
	v_cndmask_b32_e64 v132, v132, v225, s[70:71]
	v_cndmask_b32_e64 v131, v131, v225, s[66:67]
	v_cndmask_b32_e64 v161, v161, v225, s[64:65]
	v_cndmask_b32_e64 v160, v160, v225, s[62:63]
	v_cndmask_b32_e64 v159, v159, v225, s[60:61]
	v_cndmask_b32_e64 v158, v158, v225, s[58:59]
	v_cndmask_b32_e64 v157, v157, v225, s[56:57]
	v_cndmask_b32_e64 v156, v156, v225, s[54:55]
	v_cndmask_b32_e64 v155, v155, v225, s[52:53]
	v_cndmask_b32_e64 v154, v154, v225, s[50:51]
	v_cndmask_b32_e64 v153, v153, v225, s[48:49]
	v_cndmask_b32_e64 v152, v152, v225, s[46:47]
	v_cndmask_b32_e64 v151, v151, v225, s[44:45]
	v_cndmask_b32_e64 v150, v150, v225, s[42:43]
	v_cndmask_b32_e64 v149, v149, v225, s[40:41]
	v_cndmask_b32_e64 v148, v148, v225, s[36:37]
	v_cndmask_b32_e64 v147, v147, v225, s[0:1]
	v_cndmask_b32_e32 v146, v146, v225, vcc
	s_branch .LBB0_143
